# grid barrier: the released blocks' L1 invalidate moved from after phases 3 and 7 to after phases 4 and 9 (still separates every re-used buffer pair)
# baseline (speedup 1.0000x reference)
; DEVINL unsigned xb_ld(unsigned* p) { return __hip_atomic_load(p, __ATOMIC_RELAXED, __HIP_MEMORY_SCOPE_AGENT); }
; #define XB_SPIN(cond, bar) do { unsigned _sp = 0; while (cond) { __builtin_amdgcn_s_sleep(1); \
;     if ((++_sp & 255u) == 0u) { if (xb_ld(&(bar)[XB_TMO])) break; if (_sp > XB_SPIN_CAP) { atomicAdd(&(bar)[XB_TMO], 1u); break; } } } } while (0)
; DEVINL void xcd_barrier(XcdBarrier& b) {
;     ...
;     } else {
;       XB_SPIN(xb_ld(&bar[XB_XGEN(b.x)]) == gen, bar);
;       __builtin_amdgcn_fence(__ATOMIC_ACQUIRE, "agent");
;       asm volatile("s_waitcnt vmcnt(0)" ::: "memory");
;     }
; __global__ void __launch_bounds__(256, 2) mega_kernel(Params p) {
;     ...
;   for (int ph = 0; ph < NPHASE; ++ph) {
;     if (ph == 5) continue;
;     run_phase(p, smem, ph);
;     if (ph + 1 < NPHASE) xcd_barrier(xb);
.LBB0_1580:
	s_or_b64 exec, exec, s[38:39]
	s_waitcnt vmcnt(0)
	s_cmp_eq_u32 s29, 4
	s_cbranch_scc1 .LBAR_l1inv
	s_cmp_eq_u32 s29, 9
	s_cbranch_scc1 .LBAR_l1inv
	s_branch .LBAR_l1done
